# mLSTM head-norm scaling of HM streamed inside attention items 0-3 (plain stores), fix-up part 1 skipped; V loads contiguous
# speedup vs baseline: 1.0216x; 1.0024x over previous
; #define LAS __attribute__((address_space(3)))
; __device__ __forceinline__ void attn_load(const bf16_t* R1, const AttnItem& a, int tid, u32x4 (&kr)[8], u32x4 (&vr)[8]) {
;     const int lg = 2 * a.g;
;     ...
;     const bf16_t* Kq = (const bf16_t*)((const unsigned char*)R1 + R1_KA) + seq; const bf16_t* Vq = (const bf16_t*)((const unsigned char*)R1 + R1_VA) + seq;
;     const int row = tid >> 1, pv = tid & 1; const int jk = a.blk * 128 - 128 + row;
;     const u32x4 z = (u32x4){0u, 0u, 0u, 0u};
;     if (jk >= 0) { const bf16_t* src = Kq + (size_t)jk * 128; kr[0] = *(const u32x4*)(src + 8 * pv); kr[1] = *(const u32x4*)(src + 16 + 8 * pv); } else { kr[0] = z; kr[1] = z; }
; #pragma unroll
;     for (int i = 0; i < 6; ++i) {
;         const int task = tid + 512 * i; const int row2 = task / 12, v = 4 + task % 12; const int jk2 = a.blk * 128 - 128 + row2;
;         kr[2 + i] = (jk2 >= 0) ? *(const u32x4*)(Kq + (size_t)jk2 * 128 + v * 8) : z;
;     }
; #pragma unroll
;     for (int vi = 0; vi < 8; ++vi) vr[vi] = (jk >= 0) ? *(const u32x4*)(Vq + (size_t)jk * 128 + pv * 64 + vi * 8) : z;
; }
; __device__ __forceinline__ void p4_attn(const Params& p, LAS unsigned char* lds, const int dummy) {
;     const int tid = threadIdx.x, wid = __builtin_amdgcn_readfirstlane(tid >> 6), lane = tid & 63, r = lane & 15, q = lane >> 4;
;     unsigned char* ws = p.ws;
;     bf16_t* R1 = (bf16_t*)(ws + WS_R1);
;     const float* RC = (const float*)(ws + WS_ROPE); const float* RS = RC + 2048 * 16;
;     float* ML = (float*)((unsigned char*)p.out + OUT_ML);
;     LAS unsigned char* KA = lds + AT_KA; LAS unsigned char* VB = lds + AT_VB;
;     const float QSCALE = 0.08838834764831845f * 1.4426950408889634f;
;     u32x4 kr[8], vr[8];
;     int it = blockIdx.x;
;     if (it < 1536) { const AttnItem a0 = attn_item(it); attn_load(R1, a0, tid, kr, vr); }
; __device__ __forceinline__ void p5_fixup(const Params& p) {
;     ...
;     for (int v0 = gtid; v0 < T_TOK * 128; v0 += 4 * gsz) {
;         u32x4 hv[4]; float4 s0[4], s1[4];
; #pragma unroll
;         for (int u = 0; u < 4; ++u) { const int v = v0 + u * gsz; if (v < T_TOK * 128) { const int row = v >> 7, head = (v >> 5) & 3;
;             hv[u] = __builtin_nontemporal_load((const u32x4*)(HM + (size_t)v * 8)); s0[u] = *(const float4*)(SSQ + ((size_t)row * 4 + head) * 8); s1[u] = *(const float4*)(SSQ + ((size_t)row * 4 + head) * 8 + 4); } }
.LBB0_570:
	s_mov_b32 s99, 0
	s_cmp_lt_i32 s90, 6
	s_cselect_b64 s[0:1], -1, 0
	s_and_b64 s[96:97], s[0:1], s[2:3]
	s_andn2_b64 vcc, exec, s[96:97]
	s_cbranch_vccnz .LBB0_629
	s_movk_i32 s98, 0x64
	s_cmp_lg_u32 s82, 0x100
	s_cbranch_scc1 .Lhm_nofuse
	s_mov_b32 s98, 0
	s_mov_b32 s99, 1
	v_readlane_b32 s100, v254, 23
	v_readlane_b32 s101, v254, 24
	v_lshlrev_b32_e32 v250, 4, v212
	v_mov_b32_e32 v251, s84
	v_lshl_add_u32 v250, v251, 15, v250
	v_lshlrev_b32_e32 v251, 11, v251
	v_and_b32_e32 v252, 0x1e0, v212
	v_add_u32_e32 v251, v251, v252
	v_and_b32_e32 v252, 7, v212
	v_lshl_add_u32 v251, v252, 2, v251
	v_add_u32_e32 v251, 0xfd80000, v251
.Lhm_nofuse:
	v_mul_u32_u24_e32 v1, 0x1556, v212
	s_movk_i32 s1, 0xff80
	v_mov_b32_e32 v2, 12
	v_or_b32_sdwa v131, v1, s1 dst_sel:DWORD dst_unused:UNUSED_PAD src0_sel:WORD_1 src1_sel:DWORD
	v_mul_lo_u16_sdwa v1, v1, v2 dst_sel:DWORD dst_unused:UNUSED_PAD src0_sel:WORD_1 src1_sel:DWORD
	s_cmpk_lt_i32 s84, 0x600
	v_sub_u16_e32 v1, v212, v1
	s_cselect_b64 s[2:3], -1, 0
	s_add_u32 s14, s88, 0x5d80000
	v_lshlrev_b16_e32 v132, 3, v1
	v_add_u16_e32 v1, 0x200, v212
	s_addc_u32 s15, s89, 0
	v_mul_u32_u24_e32 v3, 0x1556, v1
	s_add_u32 s0, s88, 0x8d80000
	v_add_u32_sdwa v133, v3, s1 dst_sel:DWORD dst_unused:UNUSED_PAD src0_sel:WORD_1 src1_sel:DWORD
	v_mul_lo_u16_sdwa v3, v3, v2 dst_sel:DWORD dst_unused:UNUSED_PAD src0_sel:WORD_1 src1_sel:DWORD
	v_writelane_b32 v254, s0, 55
	s_addc_u32 s0, s89, 0
	v_sub_u16_e32 v1, v1, v3
	v_writelane_b32 v254, s0, 57
	s_movk_i32 s0, 0x1556
	v_lshlrev_b16_e32 v134, 3, v1
	v_or_b32_e32 v1, 0x400, v212
	v_mul_u32_u24_sdwa v3, v1, s0 dst_sel:DWORD dst_unused:UNUSED_PAD src0_sel:WORD_0 src1_sel:DWORD
	v_add_u32_sdwa v135, v3, s1 dst_sel:DWORD dst_unused:UNUSED_PAD src0_sel:WORD_1 src1_sel:DWORD
	v_mul_lo_u16_sdwa v3, v3, v2 dst_sel:DWORD dst_unused:UNUSED_PAD src0_sel:WORD_1 src1_sel:DWORD
	v_sub_u16_e32 v1, v1, v3
	v_lshlrev_b16_e32 v136, 3, v1
	v_add_u16_e32 v1, 0x600, v212
	v_mul_u32_u24_e32 v3, 0x1556, v1
	v_add_u32_sdwa v137, v3, s1 dst_sel:DWORD dst_unused:UNUSED_PAD src0_sel:WORD_1 src1_sel:DWORD
	v_mul_lo_u16_sdwa v3, v3, v2 dst_sel:DWORD dst_unused:UNUSED_PAD src0_sel:WORD_1 src1_sel:DWORD
	v_sub_u16_e32 v1, v1, v3
	v_lshlrev_b16_e32 v138, 3, v1
	v_or_b32_e32 v1, 0x800, v212
	v_mul_u32_u24_sdwa v3, v1, s0 dst_sel:DWORD dst_unused:UNUSED_PAD src0_sel:WORD_0 src1_sel:DWORD
	v_add_u32_sdwa v139, v3, s1 dst_sel:DWORD dst_unused:UNUSED_PAD src0_sel:WORD_1 src1_sel:DWORD
	v_mul_lo_u16_sdwa v3, v3, v2 dst_sel:DWORD dst_unused:UNUSED_PAD src0_sel:WORD_1 src1_sel:DWORD
	v_sub_u16_e32 v1, v1, v3
	v_lshlrev_b16_e32 v140, 3, v1
	v_add_u16_e32 v1, 0xa00, v212
	v_mul_u32_u24_e32 v3, 0x1556, v1
	v_mul_lo_u16_sdwa v2, v3, v2 dst_sel:DWORD dst_unused:UNUSED_PAD src0_sel:WORD_1 src1_sel:DWORD
	v_sub_u16_e32 v1, v1, v2
	s_cmpk_gt_i32 s84, 0x5ff
	s_waitcnt vmcnt(0)
	v_lshrrev_b32_e32 v38, 1, v212
	v_lshlrev_b32_e32 v130, 3, v190
	v_mov_b32_e32 v0, 0
	v_add_u32_sdwa v141, v3, s1 dst_sel:DWORD dst_unused:UNUSED_PAD src0_sel:WORD_1 src1_sel:DWORD
	v_lshlrev_b16_e32 v142, 3, v1
	v_lshlrev_b32_e32 v143, 6, v190
	v_readfirstlane_b32 s10, v212
	s_cbranch_scc1 .LBB0_589
	s_ashr_i32 s0, s84, 6
	s_mul_hi_i32 s5, s0, 0x55555556
	s_lshr_b32 s6, s5, 31
	s_add_i32 s5, s5, s6
	s_mul_i32 s5, s5, 3
	s_sub_i32 s0, s0, s5
	s_mul_hi_i32 s5, s84, 0x2aaaaaab
	s_lshr_b32 s6, s5, 31
	s_ashr_i32 s5, s5, 5
	s_add_i32 s5, s5, s6
	s_lshl_b32 s6, s0, 1
	s_lshr_b32 s7, 16, s6
	s_and_b32 s1, s84, 15
	s_bfe_u32 s4, s84, 0x20004
	s_add_i32 s7, s7, -1
	s_lshl_b32 s5, s5, 2
	s_and_b32 s8, s7, s1
	s_sub_i32 s7, 4, s6
	s_or_b32 s4, s5, s4
	s_lshr_b32 s7, s1, s7
	s_lshl_b32 s4, s4, s6
	s_add_i32 s4, s7, s4
	s_lshr_b32 s5, 0x800, s6
	s_mul_i32 s4, s4, s5
	s_ashr_i32 s1, s0, 31
	s_ashr_i32 s5, s4, 31
	s_lshl_b64 s[0:1], s[0:1], 23
	s_lshl_b64 s[4:5], s[4:5], 7
	s_add_u32 s0, s4, s0
	s_addc_u32 s1, s5, s1
	s_lshl_b64 s[4:5], s[0:1], 1
	s_add_u32 s6, s14, s4
	s_addc_u32 s7, s15, s5
	s_lshl_b32 s11, s8, 7
	s_add_i32 s0, s11, 0xffffff80
	v_add_u32_e32 v2, s0, v38
	v_mov_b32_e32 v3, v0
	v_cmp_lt_i32_e32 vcc, -1, v2
	v_lshlrev_b64 v[36:37], 8, v[2:3]
	v_mov_b32_e32 v1, 0
	v_mov_b32_e32 v2, 0
	v_mov_b32_e32 v3, 0
	v_mov_b32_e32 v4, 0
	v_mov_b32_e32 v5, 0
	v_mov_b32_e32 v6, 0
	v_mov_b32_e32 v7, 0
	s_and_saveexec_b64 s[0:1], vcc
	s_cbranch_execz .LBB0_574
	v_lshl_add_u64 v[0:1], s[6:7], 0, v[36:37]
	v_lshlrev_b32_e32 v2, 1, v130
	v_mov_b32_e32 v3, 0
	v_lshl_add_u64 v[8:9], v[0:1], 0, v[2:3]
	global_load_dwordx4 v[0:3], v[8:9], off
	global_load_dwordx4 v[4:7], v[8:9], off offset:32

; __device__ __forceinline__ void attn_load(const bf16_t* R1, const AttnItem& a, int tid, u32x4 (&kr)[8], u32x4 (&vr)[8]) {
;     const int lg = 2 * a.g;
;     ...
;     const bf16_t* Kq = (const bf16_t*)((const unsigned char*)R1 + R1_KA) + seq; const bf16_t* Vq = (const bf16_t*)((const unsigned char*)R1 + R1_VA) + seq;
;     const int row = tid >> 1, pv = tid & 1; const int jk = a.blk * 128 - 128 + row;
;     const u32x4 z = (u32x4){0u, 0u, 0u, 0u};
;     if (jk >= 0) { const bf16_t* src = Kq + (size_t)jk * 128; kr[0] = *(const u32x4*)(src + 8 * pv); kr[1] = *(const u32x4*)(src + 16 + 8 * pv); } else { kr[0] = z; kr[1] = z; }
; #pragma unroll
;     for (int i = 0; i < 6; ++i) {
;         const int task = tid + 512 * i; const int row2 = task / 12, v = 4 + task % 12; const int jk2 = a.blk * 128 - 128 + row2;
;         kr[2 + i] = (jk2 >= 0) ? *(const u32x4*)(Kq + (size_t)jk2 * 128 + v * 8) : z;
;     }
; #pragma unroll
;     for (int vi = 0; vi < 8; ++vi) vr[vi] = (jk >= 0) ? *(const u32x4*)(Vq + (size_t)jk * 128 + pv * 64 + vi * 8) : z;
.LBB0_580:
	s_or_b64 exec, exec, s[8:9]
	v_add_u32_e32 v24, s11, v137
	v_mov_b32_e32 v25, v20
	v_lshlrev_b64 v[24:25], 8, v[24:25]
	v_lshl_add_u64 v[24:25], s[6:7], 0, v[24:25]
	v_lshlrev_b32_e32 v26, 1, v138
	v_mov_b32_e32 v27, v20
	v_lshl_add_u64 v[40:41], v[24:25], 0, v[26:27]
	v_add_u32_e32 v24, s11, v139
	v_mov_b32_e32 v25, v20
	v_lshlrev_b64 v[24:25], 8, v[24:25]
	v_lshl_add_u64 v[24:25], s[6:7], 0, v[24:25]
	v_lshlrev_b32_e32 v26, 1, v140
	v_lshl_add_u64 v[42:43], v[24:25], 0, v[26:27]
	v_add_u32_e32 v24, s11, v141
	v_mov_b32_e32 v25, v20
	v_lshlrev_b64 v[24:25], 8, v[24:25]
	v_lshl_add_u64 v[24:25], s[6:7], 0, v[24:25]
	v_lshlrev_b32_e32 v26, 1, v142
	v_lshl_add_u64 v[44:45], v[24:25], 0, v[26:27]
	global_load_dwordx4 v[24:27], v[40:41], off offset:64
	global_load_dwordx4 v[28:31], v[42:43], off offset:64
	global_load_dwordx4 v[32:35], v[44:45], off offset:64
	v_readlane_b32 s0, v254, 55
	s_add_u32 s0, s0, s4
	v_readlane_b32 s1, v254, 57
	s_addc_u32 s1, s1, s5
	v_lshlrev_b32_e32 v36, 4, v212
	s_cmp_eq_u32 s11, 0
	s_cbranch_scc1 .Lav_h_blk0
	v_lshl_add_u32 v36, s11, 8, v36
	v_add_u32_e32 v36, 0xffff8000, v36
	global_load_dwordx4 v[20:23], v36, s[0:1]
	v_add_u32_e32 v36, 0x2000, v36
	global_load_dwordx4 v[40:43], v36, s[0:1]
	v_add_u32_e32 v36, 0x2000, v36
	global_load_dwordx4 v[48:51], v36, s[0:1]
	v_add_u32_e32 v36, 0x2000, v36
	global_load_dwordx4 v[44:47], v36, s[0:1]
	v_add_u32_e32 v36, 0x2000, v36
	s_branch .Lav_h_hi
.Lav_h_blk0:
	v_mov_b32_e32 v20, 0
	v_mov_b32_e32 v21, 0
	v_mov_b32_e32 v22, 0
	v_mov_b32_e32 v23, 0
	v_mov_b32_e32 v40, 0
	v_mov_b32_e32 v41, 0
	v_mov_b32_e32 v42, 0
	v_mov_b32_e32 v43, 0
	v_mov_b32_e32 v44, 0
	v_mov_b32_e32 v45, 0
	v_mov_b32_e32 v46, 0
	v_mov_b32_e32 v47, 0
	v_mov_b32_e32 v48, 0
	v_mov_b32_e32 v49, 0
	v_mov_b32_e32 v50, 0
	v_mov_b32_e32 v51, 0
.Lav_h_hi:
	global_load_dwordx4 v[52:55], v36, s[0:1]
	v_add_u32_e32 v36, 0x2000, v36
	global_load_dwordx4 v[56:59], v36, s[0:1]
	v_add_u32_e32 v36, 0x2000, v36
	global_load_dwordx4 v[64:67], v36, s[0:1]
	v_add_u32_e32 v36, 0x2000, v36
	global_load_dwordx4 v[60:63], v36, s[0:1]
	s_andn2_b64 vcc, exec, s[2:3]
	s_cbranch_vccz .LBB0_590
	s_branch .LBB0_629

; __device__ __forceinline__ void p5_fixup(const Params& p) {
;     ...
;     for (int v0 = gtid; v0 < T_TOK * 128; v0 += 4 * gsz) {
;         u32x4 hv[4]; float4 s0[4], s1[4];
; #pragma unroll
;         for (int u = 0; u < 4; ++u) { const int v = v0 + u * gsz; if (v < T_TOK * 128) { const int row = v >> 7, head = (v >> 5) & 3;
;             hv[u] = __builtin_nontemporal_load((const u32x4*)(HM + (size_t)v * 8)); s0[u] = *(const float4*)(SSQ + ((size_t)row * 4 + head) * 8); s1[u] = *(const float4*)(SSQ + ((size_t)row * 4 + head) * 8 + 4); } }
.Lat_norope:
	s_or_b64 exec, exec, s[0:1]
	s_cmp_gt_u32 s98, 3
	s_cbranch_scc1 .Lhm_noissue
	v_mov_b32_e32 v252, s98
	v_lshl_add_u32 v255, v252, 23, v250
	v_lshl_add_u32 v252, v252, 19, v251
	global_load_dwordx4 v[230:233], v255, s[100:101] nt
	v_add_u32_e32 v255, 0x2000, v255
	global_load_dwordx4 v[234:237], v255, s[100:101] nt
	v_add_u32_e32 v255, 0x2000, v255
	global_load_dwordx4 v[238:241], v255, s[100:101] nt
	v_add_u32_e32 v255, 0x2000, v255
	global_load_dwordx4 v[242:245], v255, s[100:101] nt
	global_load_dword v246, v252, s[88:89]
	global_load_dword v247, v252, s[88:89] offset:512
	global_load_dword v248, v252, s[88:89] offset:1024
	global_load_dword v249, v252, s[88:89] offset:1536
	s_waitcnt vmcnt(8)
	s_branch .Lhm_issued

; __device__ __forceinline__ void p4_attn(const Params& p, LAS unsigned char* lds, const int dummy) {
;     ...
;         {
;             const int row = tid >> 1, pv = tid & 1; const int jk = blk * 128 - 128 + row;
;             u32x4 o1 = kr[0], o2 = kr[1];
;             if (jk >= 0) {
;                 const int pos = jk * dil + rr;
;                 float x1[8], x2[8]; unpack8(kr[0], x1); unpack8(kr[1], x2);
;                 const float4 ca = *(const float4*)(RC + pos * 16 + 8 * pv), cb = *(const float4*)(RC + pos * 16 + 8 * pv + 4);
;                 const float4 sa = *(const float4*)(RS + pos * 16 + 8 * pv), sb = *(const float4*)(RS + pos * 16 + 8 * pv + 4);
;                 const float cc[8] = {ca.x, ca.y, ca.z, ca.w, cb.x, cb.y, cb.z, cb.w}, sn[8] = {sa.x, sa.y, sa.z, sa.w, sb.x, sb.y, sb.z, sb.w};
;                 float y1[8], y2[8];
; #pragma unroll
;                 for (int e = 0; e < 8; ++e) { y1[e] = x1[e] * cc[e] - x2[e] * sn[e]; y2[e] = x2[e] * cc[e] + x1[e] * sn[e]; }
;                 o1 = pack8(y1); o2 = pack8(y2);
;             }
.Lhm_issued:
	v_mov_b64_e32 v[102:103], v[6:7]
	v_mov_b64_e32 v[98:99], v[2:3]
	v_mov_b64_e32 v[100:101], v[4:5]
	v_mov_b64_e32 v[96:97], v[0:1]
	s_and_saveexec_b64 s[0:1], vcc
	s_cbranch_execz .LBB0_594
	v_lshlrev_b32_e32 v84, 16, v0
	v_and_b32_e32 v85, 0xffff0000, v0
	v_lshlrev_b32_e32 v86, 16, v4
	v_and_b32_e32 v87, 0xffff0000, v4
	v_pk_mul_f32 v[38:39], v[80:81], v[84:85]
	v_pk_mul_f32 v[80:81], v[80:81], v[86:87]
	v_pk_fma_f32 v[38:39], v[72:73], v[86:87], v[38:39]
	v_pk_fma_f32 v[72:73], v[72:73], v[84:85], v[80:81] neg_lo:[0,0,1] neg_hi:[0,0,1]
	v_lshlrev_b32_e32 v80, 16, v1
	v_and_b32_e32 v81, 0xffff0000, v1
	v_lshlrev_b32_e32 v84, 16, v5
	v_and_b32_e32 v85, 0xffff0000, v5
	v_pk_mul_f32 v[86:87], v[82:83], v[80:81]
	v_pk_mul_f32 v[82:83], v[82:83], v[84:85]
	v_pk_fma_f32 v[86:87], v[74:75], v[84:85], v[86:87]
	v_pk_fma_f32 v[74:75], v[74:75], v[80:81], v[82:83] neg_lo:[0,0,1] neg_hi:[0,0,1]
	v_lshlrev_b32_e32 v80, 16, v2
	v_and_b32_e32 v81, 0xffff0000, v2
	v_lshlrev_b32_e32 v82, 16, v6
	v_and_b32_e32 v83, 0xffff0000, v6
	v_pk_mul_f32 v[84:85], v[76:77], v[80:81]
	v_pk_mul_f32 v[76:77], v[76:77], v[82:83]
	v_pk_fma_f32 v[84:85], v[68:69], v[82:83], v[84:85]
	v_pk_fma_f32 v[68:69], v[68:69], v[80:81], v[76:77] neg_lo:[0,0,1] neg_hi:[0,0,1]
	v_lshlrev_b32_e32 v76, 16, v3
	v_and_b32_e32 v77, 0xffff0000, v3
	v_lshlrev_b32_e32 v80, 16, v7
	v_and_b32_e32 v81, 0xffff0000, v7
	v_pk_mul_f32 v[82:83], v[78:79], v[76:77]
	v_pk_mul_f32 v[78:79], v[78:79], v[80:81]
	v_pk_fma_f32 v[82:83], v[70:71], v[80:81], v[82:83]
	v_pk_fma_f32 v[70:71], v[70:71], v[76:77], v[78:79] neg_lo:[0,0,1] neg_hi:[0,0,1]
	v_cvt_pk_bf16_f32 v96, v72, v73
	v_cvt_pk_bf16_f32 v97, v74, v75
	v_cvt_pk_bf16_f32 v98, v68, v69
	v_cvt_pk_bf16_f32 v99, v70, v71
	v_cvt_pk_bf16_f32 v100, v38, v39
	v_cvt_pk_bf16_f32 v101, v86, v87
	v_cvt_pk_bf16_f32 v102, v84, v85
	v_cvt_pk_bf16_f32 v103, v82, v83

; __device__ __forceinline__ void st_wt16(void* p, u32x4 v) { asm volatile("global_store_dwordx4 %0, %1, off sc1\n\ts_nop 1" : : "v"(p), "v"(v) : "memory"); }
; __device__ __forceinline__ void attn_load(const bf16_t* R1, const AttnItem& a, int tid, u32x4 (&kr)[8], u32x4 (&vr)[8]) {
;     const int lg = 2 * a.g;
;     ...
;     const bf16_t* Kq = (const bf16_t*)((const unsigned char*)R1 + R1_KA) + seq; const bf16_t* Vq = (const bf16_t*)((const unsigned char*)R1 + R1_VA) + seq;
;     const int row = tid >> 1, pv = tid & 1; const int jk = a.blk * 128 - 128 + row;
;     const u32x4 z = (u32x4){0u, 0u, 0u, 0u};
;     if (jk >= 0) { const bf16_t* src = Kq + (size_t)jk * 128; kr[0] = *(const u32x4*)(src + 8 * pv); kr[1] = *(const u32x4*)(src + 16 + 8 * pv); } else { kr[0] = z; kr[1] = z; }
; #pragma unroll
;     for (int i = 0; i < 6; ++i) {
;         const int task = tid + 512 * i; const int row2 = task / 12, v = 4 + task % 12; const int jk2 = a.blk * 128 - 128 + row2;
;         kr[2 + i] = (jk2 >= 0) ? *(const u32x4*)(Kq + (size_t)jk2 * 128 + v * 8) : z;
;     }
; #pragma unroll
;     for (int vi = 0; vi < 8; ++vi) vr[vi] = (jk >= 0) ? *(const u32x4*)(Vq + (size_t)jk * 128 + pv * 64 + vi * 8) : z;
; __device__ __forceinline__ void p5_fixup(const Params& p) {
;     ...
;     for (int v0 = gtid; v0 < T_TOK * 128; v0 += 4 * gsz) {
;         u32x4 hv[4]; float4 s0[4], s1[4];
; #pragma unroll
;         for (int u = 0; u < 4; ++u) { const int v = v0 + u * gsz; if (v < T_TOK * 128) { const int row = v >> 7, head = (v >> 5) & 3;
;             hv[u] = __builtin_nontemporal_load((const u32x4*)(HM + (size_t)v * 8)); s0[u] = *(const float4*)(SSQ + ((size_t)row * 4 + head) * 8); s1[u] = *(const float4*)(SSQ + ((size_t)row * 4 + head) * 8 + 4); } }
; #pragma unroll
;         for (int u = 0; u < 4; ++u) { const int v = v0 + u * gsz; if (v < T_TOK * 128) {
;             const float ss = (s0[u].x + s0[u].y) + (s0[u].z + s0[u].w) + (s1[u].x + s1[u].y) + (s1[u].z + s1[u].w);
;             const float rstd = rsqrtf(ss * (1.0f / 256.0f) + EPS);
;             float f[8]; unpack8(hv[u], f);
; #pragma unroll
;             for (int e = 0; e < 8; ++e) f[e] *= rstd;
;             st_wt16(HM + (size_t)v * 8, pack8(f)); } }
.LBB0_603:
	s_or_b64 exec, exec, s[6:7]
	v_add_u32_e32 v22, s12, v137
	v_mov_b32_e32 v23, v36
	v_lshlrev_b64 v[22:23], 8, v[22:23]
	v_lshl_add_u64 v[22:23], s[82:83], 0, v[22:23]
	v_lshlrev_b32_e32 v24, 1, v138
	v_mov_b32_e32 v25, v36
	v_lshl_add_u64 v[22:23], v[22:23], 0, v[24:25]
	v_add_u32_e32 v24, s12, v139
	v_lshlrev_b64 v[24:25], 8, v[24:25]
	v_lshl_add_u64 v[24:25], s[82:83], 0, v[24:25]
	v_lshlrev_b32_e32 v26, 1, v140
	v_mov_b32_e32 v27, v36
	v_lshl_add_u64 v[28:29], v[24:25], 0, v[26:27]
	global_load_dwordx4 v[24:27], v[22:23], off offset:64
	s_nop 0
	global_load_dwordx4 v[28:31], v[28:29], off offset:64
	v_add_u32_e32 v22, s12, v141
	v_mov_b32_e32 v23, v36
	v_lshlrev_b64 v[22:23], 8, v[22:23]
	v_lshl_add_u64 v[22:23], s[82:83], 0, v[22:23]
	v_lshlrev_b32_e32 v32, 1, v142
	v_mov_b32_e32 v33, v36
	v_lshl_add_u64 v[22:23], v[22:23], 0, v[32:33]
	global_load_dwordx4 v[32:35], v[22:23], off offset:64
	v_readlane_b32 s0, v254, 55
	s_add_u32 s0, s0, s4
	v_readlane_b32 s1, v254, 57
	s_addc_u32 s1, s1, s5
	v_lshlrev_b32_e32 v128, 4, v212
	s_cmp_eq_u32 s12, 0
	s_cbranch_scc1 .Lav_l_blk0
	v_lshl_add_u32 v128, s12, 8, v128
	v_add_u32_e32 v128, 0xffff8000, v128
	global_load_dwordx4 v[20:23], v128, s[0:1]
	v_add_u32_e32 v128, 0x2000, v128
	global_load_dwordx4 v[40:43], v128, s[0:1]
	v_add_u32_e32 v128, 0x2000, v128
	global_load_dwordx4 v[48:51], v128, s[0:1]
	v_add_u32_e32 v128, 0x2000, v128
	global_load_dwordx4 v[44:47], v128, s[0:1]
	v_add_u32_e32 v128, 0x2000, v128
	s_branch .Lav_l_hi
.Lav_l_blk0:
	v_mov_b32_e32 v20, 0
	v_mov_b32_e32 v21, 0
	v_mov_b32_e32 v22, 0
	v_mov_b32_e32 v23, 0
	v_mov_b32_e32 v40, 0
	v_mov_b32_e32 v41, 0
	v_mov_b32_e32 v42, 0
	v_mov_b32_e32 v43, 0
	v_mov_b32_e32 v44, 0
	v_mov_b32_e32 v45, 0
	v_mov_b32_e32 v46, 0
	v_mov_b32_e32 v47, 0
	v_mov_b32_e32 v48, 0
	v_mov_b32_e32 v49, 0
	v_mov_b32_e32 v50, 0
	v_mov_b32_e32 v51, 0
.Lav_l_hi:
	global_load_dwordx4 v[52:55], v128, s[0:1]
	v_add_u32_e32 v128, 0x2000, v128
	global_load_dwordx4 v[56:59], v128, s[0:1]
	v_add_u32_e32 v128, 0x2000, v128
	global_load_dwordx4 v[64:67], v128, s[0:1]
	v_add_u32_e32 v128, 0x2000, v128
	global_load_dwordx4 v[60:63], v128, s[0:1]
.Lattn_pf_done:
	s_cmp_gt_u32 s98, 3
	s_cbranch_scc1 .Lhm_noconsume
	v_add_f32_dpp v246, v246, v246 quad_perm:[1,0,3,2] row_mask:0xf bank_mask:0xf
	v_add_f32_dpp v247, v247, v247 quad_perm:[1,0,3,2] row_mask:0xf bank_mask:0xf
	v_add_f32_dpp v248, v248, v248 quad_perm:[1,0,3,2] row_mask:0xf bank_mask:0xf
	v_add_f32_dpp v249, v249, v249 quad_perm:[1,0,3,2] row_mask:0xf bank_mask:0xf
	v_add_f32_dpp v246, v246, v246 quad_perm:[2,3,0,1] row_mask:0xf bank_mask:0xf
	v_add_f32_dpp v247, v247, v247 quad_perm:[2,3,0,1] row_mask:0xf bank_mask:0xf
	v_add_f32_dpp v248, v248, v248 quad_perm:[2,3,0,1] row_mask:0xf bank_mask:0xf
	v_add_f32_dpp v249, v249, v249 quad_perm:[2,3,0,1] row_mask:0xf bank_mask:0xf
	v_add_f32_dpp v246, v246, v246 row_half_mirror row_mask:0xf bank_mask:0xf
	v_add_f32_dpp v247, v247, v247 row_half_mirror row_mask:0xf bank_mask:0xf
	v_add_f32_dpp v248, v248, v248 row_half_mirror row_mask:0xf bank_mask:0xf
	v_add_f32_dpp v249, v249, v249 row_half_mirror row_mask:0xf bank_mask:0xf
	v_mov_b32_e32 v252, 0x358637bd
	v_mov_b32_e32 v255, s98
	v_fmamk_f32 v246, v246, 0x3b800000, v252
	v_fmamk_f32 v247, v247, 0x3b800000, v252
	v_fmamk_f32 v248, v248, 0x3b800000, v252
	v_fmamk_f32 v249, v249, 0x3b800000, v252
	v_rsq_f32_e32 v246, v246
	v_rsq_f32_e32 v247, v247
	v_rsq_f32_e32 v248, v248
	v_rsq_f32_e32 v249, v249
	v_lshl_add_u32 v255, v255, 23, v250
	v_lshlrev_b32_e32 v252, 16, v230
	v_and_b32_e32 v253, 0xffff0000, v230
	v_mul_f32_e32 v252, v246, v252
	v_mul_f32_e32 v253, v246, v253
	v_cvt_pk_bf16_f32 v230, v252, v253
	v_lshlrev_b32_e32 v252, 16, v231
	v_and_b32_e32 v253, 0xffff0000, v231
	v_mul_f32_e32 v252, v246, v252
	v_mul_f32_e32 v253, v246, v253
	v_cvt_pk_bf16_f32 v231, v252, v253
	v_lshlrev_b32_e32 v252, 16, v232
	v_and_b32_e32 v253, 0xffff0000, v232
	v_mul_f32_e32 v252, v246, v252
	v_mul_f32_e32 v253, v246, v253
	v_cvt_pk_bf16_f32 v232, v252, v253
	v_lshlrev_b32_e32 v252, 16, v233
	v_and_b32_e32 v253, 0xffff0000, v233
	v_mul_f32_e32 v252, v246, v252
	v_mul_f32_e32 v253, v246, v253
	v_cvt_pk_bf16_f32 v233, v252, v253
	global_store_dwordx4 v255, v[230:233], s[100:101]
	v_add_u32_e32 v255, 0x2000, v255
	v_lshlrev_b32_e32 v252, 16, v234
	v_and_b32_e32 v253, 0xffff0000, v234
	v_mul_f32_e32 v252, v247, v252
	v_mul_f32_e32 v253, v247, v253
	v_cvt_pk_bf16_f32 v234, v252, v253
	v_lshlrev_b32_e32 v252, 16, v235
	v_and_b32_e32 v253, 0xffff0000, v235
	v_mul_f32_e32 v252, v247, v252
	v_mul_f32_e32 v253, v247, v253
	v_cvt_pk_bf16_f32 v235, v252, v253
	v_lshlrev_b32_e32 v252, 16, v236
	v_and_b32_e32 v253, 0xffff0000, v236
	v_mul_f32_e32 v252, v247, v252
	v_mul_f32_e32 v253, v247, v253
	v_cvt_pk_bf16_f32 v236, v252, v253
	v_lshlrev_b32_e32 v252, 16, v237
	v_and_b32_e32 v253, 0xffff0000, v237
	v_mul_f32_e32 v252, v247, v252
	v_mul_f32_e32 v253, v247, v253
	v_cvt_pk_bf16_f32 v237, v252, v253
	global_store_dwordx4 v255, v[234:237], s[100:101]
	v_add_u32_e32 v255, 0x2000, v255
	v_lshlrev_b32_e32 v252, 16, v238
	v_and_b32_e32 v253, 0xffff0000, v238
	v_mul_f32_e32 v252, v248, v252
	v_mul_f32_e32 v253, v248, v253
	v_cvt_pk_bf16_f32 v238, v252, v253
	v_lshlrev_b32_e32 v252, 16, v239
	v_and_b32_e32 v253, 0xffff0000, v239
	v_mul_f32_e32 v252, v248, v252
	v_mul_f32_e32 v253, v248, v253
	v_cvt_pk_bf16_f32 v239, v252, v253
	v_lshlrev_b32_e32 v252, 16, v240
	v_and_b32_e32 v253, 0xffff0000, v240
	v_mul_f32_e32 v252, v248, v252
	v_mul_f32_e32 v253, v248, v253
	v_cvt_pk_bf16_f32 v240, v252, v253
	v_lshlrev_b32_e32 v252, 16, v241
	v_and_b32_e32 v253, 0xffff0000, v241
	v_mul_f32_e32 v252, v248, v252
	v_mul_f32_e32 v253, v248, v253
	v_cvt_pk_bf16_f32 v241, v252, v253
	global_store_dwordx4 v255, v[238:241], s[100:101]
	v_add_u32_e32 v255, 0x2000, v255
	v_lshlrev_b32_e32 v252, 16, v242
	v_and_b32_e32 v253, 0xffff0000, v242
	v_mul_f32_e32 v252, v249, v252
	v_mul_f32_e32 v253, v249, v253
	v_cvt_pk_bf16_f32 v242, v252, v253
	v_lshlrev_b32_e32 v252, 16, v243
	v_and_b32_e32 v253, 0xffff0000, v243
	v_mul_f32_e32 v252, v249, v252
	v_mul_f32_e32 v253, v249, v253
	v_cvt_pk_bf16_f32 v243, v252, v253
	v_lshlrev_b32_e32 v252, 16, v244
	v_and_b32_e32 v253, 0xffff0000, v244
	v_mul_f32_e32 v252, v249, v252
	v_mul_f32_e32 v253, v249, v253
	v_cvt_pk_bf16_f32 v244, v252, v253
	v_lshlrev_b32_e32 v252, 16, v245
	v_and_b32_e32 v253, 0xffff0000, v245
	v_mul_f32_e32 v252, v249, v252
	v_mul_f32_e32 v253, v249, v253
	v_cvt_pk_bf16_f32 v245, v252, v253
	global_store_dwordx4 v255, v[242:245], s[100:101]
	s_nop 1

; __device__ __forceinline__ unsigned cvt_pk_bf16(float lo, float hi) { const f32x2_t f = {lo, hi}; const bf16x2_t b = __builtin_convertvector(f, bf16x2_t); return __builtin_bit_cast(unsigned, b); }
; __device__ __forceinline__ void p4_attn(const Params& p, LAS unsigned char* lds, const int dummy) {
;     ...
;         for (int ps = 0; ps < 5; ++ps) {
;             if (2 * ps + 1 >= ilo) {
;                 u32x4 bw; bw.x = cvt_pk_bf16(sT[2 * ps][0], sT[2 * ps][1]); bw.y = cvt_pk_bf16(sT[2 * ps][2], sT[2 * ps][3]);
;                 if (ps < 4) { bw.z = cvt_pk_bf16(sT[(2 * ps + 1) % 9][0], sT[(2 * ps + 1) % 9][1]); bw.w = cvt_pk_bf16(sT[(2 * ps + 1) % 9][2], sT[(2 * ps + 1) % 9][3]); } else { bw.z = 0u; bw.w = 0u; }
;                 const bf16x8 bfrag = __builtin_bit_cast(bf16x8, bw);
;                 u32x2 vlo[8], vhi[8];
; #pragma unroll
;                 for (int et = 0; et < 8; ++et) {
;                     vlo[et] = tr_read(VB + (16 * (wid + 2 * ps) + 4 * q + (r >> 2)) * VB_STRIDE + (16 * et + 4 * (r & 3)) * 2);
;                     vhi[et] = (u32x2){0u, 0u};
;                     if (ps < 4) vhi[et] = tr_read(VB + (16 * (wid + 2 * ps + 1) + 4 * q + (r >> 2)) * VB_STRIDE + (16 * et + 4 * (r & 3)) * 2);
;                 }
;                 __builtin_amdgcn_sched_barrier(0);
; #pragma unroll
;                 for (int et = 0; et < 8; ++et) {
;                     u32x4 aw; aw.x = vlo[et].x; aw.y = vlo[et].y; aw.z = vhi[et].x; aw.w = vhi[et].y;
;                     oacc[et] = __builtin_amdgcn_mfma_f32_16x16x32_bf16(__builtin_bit_cast(bf16x8, aw), bfrag, oacc[et], 0, 0, 0);
;                 }
;                 __builtin_amdgcn_sched_barrier(0);
;             }
;         }
;         const float rl = 1.0f / lsum;
;         {
;             bf16_t* odst = dummy ? (bf16_t*)((unsigned char*)p.out + 8388608 + ((tq * 1536 + qcol) * 2 & 16777215)) : R1 + tq * QZ_LD + qcol;
; #pragma unroll
;             for (int et = 0; et < 8; ++et) {
;                 u32x2 w; w.x = cvt_pk_bf16(oacc[et][0] * rl, oacc[et][1] * rl); w.y = cvt_pk_bf16(oacc[et][2] * rl, oacc[et][3] * rl);
;                 *(u32x2*)(odst + 16 * et + 4 * q) = w;
;             }
;             if (q == 0) { float2 mlv; mlv.x = mx; mlv.y = lsum; *(float2*)(ML + (tq * 12 + g * 4 + hh) * 2) = mlv; }
.LBB0_626:
	s_add_i32 s98, s98, 1
	ds_read_b64_tr_b16 v[104:105], v197
	ds_read_b64_tr_b16 v[108:109], v197 offset:32
	ds_read_b64_tr_b16 v[202:203], v197 offset:64
	ds_read_b64_tr_b16 v[206:207], v197 offset:96
	ds_read_b64_tr_b16 v[214:215], v197 offset:128
	ds_read_b64_tr_b16 v[218:219], v197 offset:160
	ds_read_b64_tr_b16 v[222:223], v197 offset:192
	ds_read_b64_tr_b16 v[226:227], v197 offset:224
	v_cvt_pk_bf16_f32 v100, v100, v101
	v_cvt_pk_bf16_f32 v101, v102, v103
	v_mov_b32_e32 v102, v36
	v_mov_b32_e32 v103, v36
	v_mov_b32_e32 v106, v36
	v_mov_b32_e32 v107, v36
	v_mov_b32_e32 v110, v36
	v_mov_b32_e32 v111, v36
	v_mov_b32_e32 v204, v36
	v_mov_b32_e32 v205, v36
	v_mov_b32_e32 v208, v36
	v_mov_b32_e32 v209, v36
	v_mov_b32_e32 v216, v36
	v_mov_b32_e32 v217, v36
	v_mov_b32_e32 v220, v36
	v_mov_b32_e32 v221, v36
	v_mov_b32_e32 v224, v36
	v_mov_b32_e32 v225, v36
	v_mov_b32_e32 v228, v36
	v_mov_b32_e32 v229, v36
	s_waitcnt lgkmcnt(7)
	v_mfma_f32_16x16x32_bf16 v[96:99], v[104:107], v[100:103], v[96:99]
	s_waitcnt lgkmcnt(6)
	v_mfma_f32_16x16x32_bf16 v[92:95], v[108:111], v[100:103], v[92:95]
	s_waitcnt lgkmcnt(5)
	v_mfma_f32_16x16x32_bf16 v[88:91], v[202:205], v[100:103], v[88:91]
	s_waitcnt lgkmcnt(4)
	v_mfma_f32_16x16x32_bf16 v[84:87], v[206:209], v[100:103], v[84:87]
	s_waitcnt lgkmcnt(3)
	v_mfma_f32_16x16x32_bf16 v[80:83], v[214:217], v[100:103], v[80:83]
	s_waitcnt lgkmcnt(2)
	v_mfma_f32_16x16x32_bf16 v[76:79], v[218:221], v[100:103], v[76:79]
	s_waitcnt lgkmcnt(1)
	v_mfma_f32_16x16x32_bf16 v[72:75], v[222:225], v[100:103], v[72:75]
	s_waitcnt lgkmcnt(0)
	v_mfma_f32_16x16x32_bf16 v[68:71], v[226:229], v[100:103], v[68:71]
	v_add_f32_e32 v39, v37, v39
	v_div_scale_f32 v37, s[0:1], v39, v39, 1.0
	v_rcp_f32_e32 v100, v37
	v_div_scale_f32 v101, vcc, 1.0, v39, 1.0
	v_mov_b32_e32 v123, v36
	v_fma_f32 v102, -v37, v100, 1.0
	v_fmac_f32_e32 v100, v102, v100
	v_mul_f32_e32 v102, v101, v100
	v_fma_f32 v103, -v37, v102, v101
	v_fmac_f32_e32 v102, v103, v100
	v_fma_f32 v37, -v37, v102, v101
	v_div_fmas_f32 v37, v37, v100, v102
	v_div_fixup_f32 v100, v37, v39, 1.0
	v_pk_mul_f32 v[96:97], v[100:101], v[96:97] op_sel_hi:[0,1]
	v_pk_mul_f32 v[98:99], v[100:101], v[98:99] op_sel_hi:[0,1]
	v_pk_mul_f32 v[92:93], v[100:101], v[92:93] op_sel_hi:[0,1]
	v_pk_mul_f32 v[94:95], v[100:101], v[94:95] op_sel_hi:[0,1]
	v_pk_mul_f32 v[88:89], v[100:101], v[88:89] op_sel_hi:[0,1]
	v_pk_mul_f32 v[90:91], v[100:101], v[90:91] op_sel_hi:[0,1]
	v_pk_mul_f32 v[84:85], v[100:101], v[84:85] op_sel_hi:[0,1]
	v_pk_mul_f32 v[86:87], v[100:101], v[86:87] op_sel_hi:[0,1]
	v_pk_mul_f32 v[80:81], v[100:101], v[80:81] op_sel_hi:[0,1]
	v_pk_mul_f32 v[82:83], v[100:101], v[82:83] op_sel_hi:[0,1]
	v_pk_mul_f32 v[76:77], v[100:101], v[76:77] op_sel_hi:[0,1]
	v_pk_mul_f32 v[78:79], v[100:101], v[78:79] op_sel_hi:[0,1]
	v_pk_mul_f32 v[72:73], v[100:101], v[72:73] op_sel_hi:[0,1]
	v_pk_mul_f32 v[74:75], v[100:101], v[74:75] op_sel_hi:[0,1]
	v_pk_mul_f32 v[68:69], v[100:101], v[68:69] op_sel_hi:[0,1]
	v_pk_mul_f32 v[70:71], v[100:101], v[70:71] op_sel_hi:[0,1]
	v_lshl_add_u64 v[102:103], v[126:127], 0, v[122:123]
	v_cvt_pk_bf16_f32 v96, v96, v97
	v_cvt_pk_bf16_f32 v97, v98, v99
	v_cvt_pk_bf16_f32 v92, v92, v93
	v_cvt_pk_bf16_f32 v93, v94, v95
	v_cvt_pk_bf16_f32 v88, v88, v89
	v_cvt_pk_bf16_f32 v89, v90, v91
	v_cvt_pk_bf16_f32 v84, v84, v85
	v_cvt_pk_bf16_f32 v85, v86, v87
	v_cvt_pk_bf16_f32 v80, v80, v81
	v_cvt_pk_bf16_f32 v81, v82, v83
	v_cvt_pk_bf16_f32 v76, v76, v77
	v_cvt_pk_bf16_f32 v77, v78, v79
	v_cvt_pk_bf16_f32 v72, v72, v73
	v_cvt_pk_bf16_f32 v73, v74, v75
	v_cvt_pk_bf16_f32 v68, v68, v69
	v_cvt_pk_bf16_f32 v69, v70, v71
	global_store_dwordx2 v[102:103], v[96:97], off
	global_store_dwordx2 v[102:103], v[92:93], off offset:32
	global_store_dwordx2 v[102:103], v[88:89], off offset:64
	global_store_dwordx2 v[102:103], v[84:85], off offset:96
	global_store_dwordx2 v[102:103], v[80:81], off offset:128
	global_store_dwordx2 v[102:103], v[76:77], off offset:160
	global_store_dwordx2 v[102:103], v[72:73], off offset:192
	global_store_dwordx2 v[102:103], v[68:69], off offset:224
	s_and_saveexec_b64 s[0:1], s[16:17]
	s_cbranch_execz .LBB0_591
	s_lshl_b32 s4, s9, 2
	s_ashr_i32 s5, s4, 31
	v_mov_b32_e32 v68, s4
	v_mov_b32_e32 v69, s5
	v_mad_i64_i32 v[68:69], s[4:5], v124, 12, v[68:69]
	s_mov_b32 s4, s14
	s_mov_b32 s5, s15
	s_mov_b64 s[6:7], s[16:17]
	s_mov_b32 s9, s18
	v_readlane_b32 s12, v254, 29
	v_or_b32_e32 v68, s10, v68
	v_readlane_b32 s14, v254, 31
	v_readlane_b32 s15, v254, 32
	v_readlane_b32 s16, v254, 33
	v_readlane_b32 s17, v254, 34
	v_readlane_b32 s18, v254, 35
	v_readlane_b32 s19, v254, 36
	s_mov_b64 s[16:17], s[6:7]
	s_mov_b32 s15, s5
	s_mov_b32 s14, s4
	v_lshl_add_u64 v[68:69], v[68:69], 3, s[18:19]
	s_mov_b32 s18, s9
	v_readlane_b32 s13, v254, 30
	global_store_dwordx2 v[68:69], v[38:39], off
	s_branch .LBB0_591

; __device__ __forceinline__ void p5_fixup(const Params& p) {
;     const int tid = threadIdx.x, G = gridDim.x, bid = blockIdx.x;
;     unsigned char* ws = p.ws;
;     const bf16_t* R1 = (const bf16_t*)(ws + WS_R1);
;     const float* SSQ = (const float*)(ws + WS_SSQ);
;     bf16_t* HM = (bf16_t*)((unsigned char*)p.out + OUT_HM);
;     const float* ML = (const float*)((unsigned char*)p.out + OUT_ML);
;     bf16_t* ATT = (bf16_t*)((unsigned char*)p.out + OUT_ATT);
;     const int gtid = bid * 512 + tid, gsz = G * 512;
;     for (int v0 = gtid; v0 < T_TOK * 128; v0 += 4 * gsz) {
;         u32x4 hv[4]; float4 s0[4], s1[4];
; #pragma unroll
;         for (int u = 0; u < 4; ++u) { const int v = v0 + u * gsz; if (v < T_TOK * 128) { const int row = v >> 7, head = (v >> 5) & 3;
;             hv[u] = __builtin_nontemporal_load((const u32x4*)(HM + (size_t)v * 8)); s0[u] = *(const float4*)(SSQ + ((size_t)row * 4 + head) * 8); s1[u] = *(const float4*)(SSQ + ((size_t)row * 4 + head) * 8 + 4); } }
; #pragma unroll
;         for (int u = 0; u < 4; ++u) { const int v = v0 + u * gsz; if (v < T_TOK * 128) {
.LBB0_679:
	s_cmp_lt_i32 s90, 7
	s_cselect_b64 s[2:3], -1, 0
	s_add_u32 s6, s74, 0x400000
	s_addc_u32 s7, s75, 0
	s_and_b64 s[8:9], s[2:3], s[0:1]
	s_andn2_b64 vcc, exec, s[8:9]
	s_cbranch_vccnz .LBB0_703
	s_waitcnt vmcnt(0)
	v_lshl_add_u32 v48, s84, 9, v212
	s_mov_b32 s17, 0x200000
	s_lshl_b32 s16, s82, 9
	v_cmp_gt_i32_e32 vcc, s17, v48
	s_cmp_eq_u32 s99, 1
	s_cselect_b64 vcc, 0, vcc
	s_and_saveexec_b64 s[10:11], vcc
	s_cbranch_execz .LBB0_695
	s_add_u32 s12, s88, 0xfd80000
	s_addc_u32 s13, s89, 0
	s_add_i32 s21, s16, s16
	s_lshl_b32 s18, s82, 10
	s_mul_i32 s19, s82, 0x600
	s_mov_b64 s[14:15], 0
	v_mov_b32_e32 v51, 0
	v_mov_b32_e32 v49, 0x358637bd
	s_mov_b32 s20, 0x800000
	s_add_i32 s21, s21, s16
	s_mov_b32 s22, 0x1fffff
	v_mov_b32_e32 v12, v48
	s_branch .LBB0_683

; #define LAS __attribute__((address_space(3)))
; __global__ void __launch_bounds__(512, 2) mega_fwd(Params p) {
;     extern __shared__ __attribute__((aligned(16))) unsigned char lds_raw[];
;     LAS unsigned char* lds = (LAS unsigned char*)lds_raw;
	.amdhsa_kernel _Z8mega_fwd6Params
		.amdhsa_group_segment_fixed_size 0
		.amdhsa_private_segment_fixed_size 0
		.amdhsa_kernarg_size 368
		.amdhsa_user_sgpr_count 2
		.amdhsa_user_sgpr_dispatch_ptr 0
		.amdhsa_user_sgpr_queue_ptr 0
		.amdhsa_user_sgpr_kernarg_segment_ptr 1
		.amdhsa_user_sgpr_dispatch_id 0
		.amdhsa_user_sgpr_kernarg_preload_length 0
		.amdhsa_user_sgpr_kernarg_preload_offset 0
		.amdhsa_user_sgpr_private_segment_size 0
		.amdhsa_uses_dynamic_stack 0
		.amdhsa_enable_private_segment 0
		.amdhsa_system_sgpr_workgroup_id_x 1
		.amdhsa_system_sgpr_workgroup_id_y 0
		.amdhsa_system_sgpr_workgroup_id_z 0
		.amdhsa_system_sgpr_workgroup_info 0
		.amdhsa_system_vgpr_workitem_id 2
		.amdhsa_next_free_vgpr 256
		.amdhsa_next_free_sgpr 102
		.amdhsa_accum_offset 256
		.amdhsa_reserve_vcc 1
		.amdhsa_float_round_mode_32 0
		.amdhsa_float_round_mode_16_64 0
		.amdhsa_float_denorm_mode_32 3
		.amdhsa_float_denorm_mode_16_64 3
		.amdhsa_dx10_clamp 1
		.amdhsa_ieee_mode 1
		.amdhsa_fp16_overflow 0
		.amdhsa_tg_split 0
		.amdhsa_exception_fp_ieee_invalid_op 0
		.amdhsa_exception_fp_denorm_src 0
		.amdhsa_exception_fp_ieee_div_zero 0
		.amdhsa_exception_fp_ieee_overflow 0
		.amdhsa_exception_fp_ieee_underflow 0
		.amdhsa_exception_fp_ieee_inexact 0
		.amdhsa_exception_int_div_zero 0
	.end_amdhsa_kernel

; #define LAS __attribute__((address_space(3)))
; __global__ void __launch_bounds__(512, 2) mega_fwd(Params p) {
;     extern __shared__ __attribute__((aligned(16))) unsigned char lds_raw[];
;     LAS unsigned char* lds = (LAS unsigned char*)lds_raw;
amdhsa.kernels:
  - .agpr_count:     0
    .args:
      - .offset:         0
        .size:           112
        .value_kind:     by_value
      - .offset:         112
        .size:           4
        .value_kind:     hidden_block_count_x
      - .offset:         116
        .size:           4
        .value_kind:     hidden_block_count_y
      - .offset:         120
        .size:           4
        .value_kind:     hidden_block_count_z
      - .offset:         124
        .size:           2
        .value_kind:     hidden_group_size_x
      - .offset:         126
        .size:           2
        .value_kind:     hidden_group_size_y
      - .offset:         128
        .size:           2
        .value_kind:     hidden_group_size_z
      - .offset:         130
        .size:           2
        .value_kind:     hidden_remainder_x
      - .offset:         132
        .size:           2
        .value_kind:     hidden_remainder_y
      - .offset:         134
        .size:           2
        .value_kind:     hidden_remainder_z
      - .offset:         152
        .size:           8
        .value_kind:     hidden_global_offset_x
      - .offset:         160
        .size:           8
        .value_kind:     hidden_global_offset_y
      - .offset:         168
        .size:           8
        .value_kind:     hidden_global_offset_z
      - .offset:         176
        .size:           2
        .value_kind:     hidden_grid_dims
      - .offset:         200
        .size:           8
        .value_kind:     hidden_multigrid_sync_arg
      - .offset:         232
        .size:           4
        .value_kind:     hidden_dynamic_lds_size
    .group_segment_fixed_size: 0
    .kernarg_segment_align: 8
    .kernarg_segment_size: 368
    .language:       OpenCL C
    .language_version:
      - 2
      - 0
    .max_flat_workgroup_size: 512
    .name:           _Z8mega_fwd6Params
    .private_segment_fixed_size: 0
    .sgpr_count:     108
    .sgpr_spill_count: 86
    .symbol:         _Z8mega_fwd6Params.kd
    .uniform_work_group_size: 1
    .uses_dynamic_stack: false
    .vgpr_count:     256
    .vgpr_spill_count: 0
    .wavefront_size: 64
